# P4: ccom constants in SGPRs, unit ticket via ds ops without store drain, merged table-load waits; P5: no full drain after gate loads (on top of fused lean tile)
# speedup vs baseline: 1.0251x; 1.0040x over previous
.LBB0_553:
	s_or_b64 exec, exec, s[0:1]
	s_add_u32 s86, s96, 0x12000000
	s_addc_u32 s87, s97, 0
	s_add_u32 s88, s96, 0xa000000
	s_addc_u32 s89, s97, 0
	s_add_u32 s98, s96, 0x1000000
	s_addc_u32 s99, s97, 0
	s_add_u32 s0, s96, 0xe00000
	v_writelane_b32 v243, s0, 5
	s_addc_u32 s0, s97, 0
	v_writelane_b32 v243, s0, 6
	s_add_u32 s0, s96, 0xf00000
	v_writelane_b32 v243, s0, 7
	s_addc_u32 s0, s97, 0
	v_writelane_b32 v243, s0, 8
	s_add_u32 s0, s96, 0x180000
	s_addc_u32 s1, s97, 0
	s_load_dwordx2 s[100:101], s[0:1], 0xae68
	v_writelane_b32 v243, s0, 9
	s_mov_b64 s[84:85], src_shared_base
	v_mov_b32_e32 v2, 0
	v_writelane_b32 v243, s1, 10
	s_add_u32 s0, s96, 0x18ae60
	s_addc_u32 s1, s97, 0
	v_writelane_b32 v243, s0, 11
	s_movk_i32 s90, 0x60
	v_mov_b32_e32 v1, 1
	v_writelane_b32 v243, s1, 12
	s_add_u32 s0, s96, 0x18ae68
	s_addc_u32 s1, s97, 0
	v_writelane_b32 v243, s0, 13
	v_mov_b32_e32 v190, 0xff800000
	v_mov_b32_e32 v191, 0x3a0
	v_writelane_b32 v243, s1, 14
	s_add_u32 s0, s96, 0x18ae6c
	s_addc_u32 s1, s97, 0
	v_writelane_b32 v243, s0, 15
	s_waitcnt vmcnt(0) lgkmcnt(0)
	s_barrier
	v_writelane_b32 v243, s1, 16
	s_add_u32 s0, s96, 0xe0e000
	v_writelane_b32 v243, s0, 17
	s_addc_u32 s0, s97, 0
	v_writelane_b32 v243, s0, 18
	s_add_u32 s0, s96, 0x1c000040
	s_addc_u32 s1, s97, 0
	v_writelane_b32 v243, s0, 19
	s_add_i32 s84, 0, 0x24240
	s_nop 0
	v_writelane_b32 v243, s1, 20
	s_mov_b32 s0, 0
	v_writelane_b32 v243, s0, 21
	s_nop 1
	v_writelane_b32 v243, s1, 22
	v_writelane_b32 v243, s2, 23
	v_writelane_b32 v243, s3, 24
	v_writelane_b32 v243, s91, 25
	v_writelane_b32 v243, s92, 26
	s_nop 1
	v_writelane_b32 v243, s93, 27
	v_writelane_b32 v243, s94, 28
	s_nop 1
	v_writelane_b32 v243, s95, 29
	v_writelane_b32 v243, s96, 30
	s_nop 1
	v_writelane_b32 v243, s97, 31
	v_writelane_b32 v243, s82, 32
	s_nop 1
	v_writelane_b32 v243, s83, 33
	v_writelane_b32 v243, s84, 34
	s_nop 1
	v_writelane_b32 v243, s85, 35
	v_writelane_b32 v243, s86, 36
	s_nop 1
	v_writelane_b32 v243, s87, 37
	v_writelane_b32 v243, s88, 38
	s_nop 1
	v_writelane_b32 v243, s89, 39
	v_writelane_b32 v243, s98, 40
	s_nop 1
	v_writelane_b32 v243, s99, 41
	v_writelane_b32 v243, s84, 42
	s_branch .LBB0_556

.LBB0_556:
	s_cmp_lg_u32 s84, -1
	s_cselect_b32 s0, s84, 0
	s_cselect_b32 s1, s85, 0
	v_mov_b32_e32 v4, s0
	v_mov_b32_e32 v5, s1
	v_mov_b32_e32 v4, 0x24240
	ds_read_b32 v3, v4
	s_mov_b64 s[0:1], -1
	s_waitcnt lgkmcnt(0)
	s_barrier
	v_readfirstlane_b32 s4, v3
	s_cmpk_gt_i32 s4, 0x5ff
	s_cbranch_scc1 .LBB0_555
	v_readlane_b32 s0, v243, 11
	v_mov_b32_e32 v192, v0
	v_readlane_b32 s1, v243, 12
	s_cmpk_gt_i32 s4, 0x1ff
	v_readfirstlane_b32 s25, v192
	s_nop 2
	global_load_dword v18, v2, s[0:1]
	s_cselect_b64 s[0:1], -1, 0
	s_add_i32 s5, s4, 0xfffffe00
	s_cmpk_lt_i32 s4, 0x200
	v_writelane_b32 v243, s0, 43
	s_cselect_b64 s[2:3], -1, 0
	v_cndmask_b32_e64 v3, 0, 1, s[2:3]
	v_writelane_b32 v243, s1, 44
	s_and_b64 s[0:1], s[2:3], exec
	s_cselect_b32 s6, s4, s5
	s_movk_i32 s0, 0x1d0
	s_and_b32 s26, s6, 1
	v_cmp_gt_i32_e32 vcc, s0, v192
	v_cmp_ne_u32_e64 s[4:5], 1, v3
	s_and_saveexec_b64 s[0:1], vcc
	s_cbranch_execz .Ltp_a
	s_and_b64 s[8:9], s[2:3], exec
	s_cselect_b32 s7, 8, 0
	s_lshl_b32 s8, s26, 2
	s_or_b32 s7, s8, s7
	s_mulk_i32 s7, 0x740
	v_readlane_b32 s8, v243, 9
	v_readlane_b32 s9, v243, 10
	s_add_u32 s8, s8, s7
	v_lshlrev_b32_e32 v4, 2, v192
	s_addc_u32 s9, s9, 0
	v_ashrrev_i32_e32 v5, 31, v4
	v_lshl_add_u64 v[6:7], v[4:5], 2, s[8:9]
	global_load_dwordx4 v[6:9], v[6:7], off
	s_and_b64 vcc, exec, s[4:5]
	s_cbranch_vccnz .Ltp_a
	s_mul_i32 s7, s26, 0x1d00
	v_readlane_b32 s8, v243, 9
	v_readlane_b32 s9, v243, 10
	s_add_u32 s8, s8, s7
	s_addc_u32 s9, s9, 0
	v_lshl_add_u64 v[10:11], v[4:5], 2, s[8:9]
	v_add_co_u32_e32 v10, vcc, 0x7000, v10
	s_nop 1
	v_addc_co_u32_e32 v11, vcc, 0, v11, vcc
	global_load_dwordx4 v[10:13], v[10:11], off offset:1024
.Ltp_a:
	s_or_b64 exec, exec, s[0:1]
	v_cmp_gt_i32_e32 vcc, 4, v192
	s_and_saveexec_b64 s[0:1], vcc
	s_cbranch_execz .Ltp_b
	s_lshl_b32 s7, s26, 2
	s_and_b64 s[8:9], s[2:3], exec
	s_movk_i32 s8, 0x2b88
	s_cselect_b32 s8, s8, 0x2b80
	s_or_b32 s7, s7, s8
	v_add_u32_e32 v4, s7, v192
	v_readlane_b32 s8, v243, 9
	v_ashrrev_i32_e32 v5, 31, v4
	v_readlane_b32 s9, v243, 10
	s_nop 1
	v_lshl_add_u64 v[4:5], v[4:5], 2, s[8:9]
	global_load_dword v14, v[4:5], off
.Ltp_b:
	s_or_b64 exec, exec, s[0:1]
	s_waitcnt vmcnt(0)
	v_cmp_gt_i32_e32 vcc, 0x1d0, v192
	s_and_saveexec_b64 s[0:1], vcc
	s_cbranch_execz .Ltp_c
	v_lshl_add_u32 v3, v192, 4, 0
	v_add_u32_e32 v3, 0x20800, v3
	ds_write_b128 v3, v[6:9]
	s_and_b64 vcc, exec, s[4:5]
	s_cbranch_vccnz .Ltp_c
	v_lshl_add_u32 v3, v192, 4, 0
	v_add_u32_e32 v3, 0x22500, v3
	ds_write_b128 v3, v[10:13]
.Ltp_c:
	s_or_b64 exec, exec, s[0:1]
	v_cmp_gt_i32_e32 vcc, 4, v192
	s_and_saveexec_b64 s[0:1], vcc
	s_cbranch_execz .Ltp_d
	v_lshl_add_u32 v4, v192, 2, 0
	v_add_u32_e32 v4, 0x24200, v4
	ds_write_b32 v4, v14

.LBB0_631:
	s_mov_b32 s34, s101
	s_add_i32 s21, s39, 0x22500
	s_add_i32 s36, 0, 0x22500
	s_add_i32 s38, s1, 0x22500
	s_mov_b64 s[28:29], 0
	s_mov_b32 s70, s57
	s_mov_b32 s71, s58
	v_mov_b32_e32 v212, v203
	s_branch .LBB0_637

.LBB0_636:
	s_mov_b32 s34, s100
	s_add_i32 s36, 0, 0x20800
	s_mov_b32 s70, 0
	v_mov_b32_e32 v212, 0
	s_mov_b32 s71, 0
	s_andn2_b64 vcc, exec, s[30:31]
	s_cbranch_vccnz .LBB0_632
.LBB0_637:
	v_mov_b32_e32 v84, s34
	s_add_i32 s30, s36, s39
	s_add_i32 s1, s36, s1
	v_mov_b32_e32 v3, s30
	v_mov_b32_e32 v4, s1
	ds_read_b32 v3, v3 offset:252
	ds_read_b32 v4, v4 offset:252
	s_mov_b64 s[36:37], 0
	s_mov_b32 s72, s33
	s_mov_b32 s73, s51
	s_mov_b64 s[30:31], 0
	s_waitcnt lgkmcnt(0)
	v_sub_f32_e32 v3, v3, v84
	v_sub_f32_e32 v4, v4, v84
	v_exp_f32_e32 v184, v3
	v_exp_f32_e32 v182, v4

.LBB0_692:
	s_nop 0
	v_cmp_eq_u32_e32 vcc, 0, v192
	s_and_saveexec_b64 s[0:1], vcc
	s_cbranch_execz .LBB0_554
	s_cmp_lg_u32 s84, -1
	s_cselect_b32 s2, s84, 0
	s_cselect_b32 s3, s85, 0
	v_mov_b32_e32 v4, s2
	v_mov_b32_e32 v5, s3
	v_mov_b32_e32 v4, 0x24240
	ds_write_b32 v4, v205
	s_branch .LBB0_554

.LBB0_769:
	s_lshr_b32 s25, s34, 4
	s_mul_i32 s36, s25, 0xc00
	s_ashr_i32 s37, s36, 31
	v_lshl_or_b32 v128, s58, 8, v162
	s_lshl_b64 s[36:37], s[36:37], 2
	s_add_u32 s36, s6, s36
	v_ashrrev_i32_e32 v129, 31, v128
	v_lshl_add_u32 v214, s34, 8, v160
	s_addc_u32 s37, s7, s37
	v_lshlrev_b64 v[156:157], 2, v[128:129]
	v_or_b32_e32 v182, 16, v214
	v_lshl_add_u64 v[128:129], s[36:37], 0, v[156:157]
	v_ashrrev_i32_e32 v215, 31, v214
	v_ashrrev_i32_e32 v183, 31, v182
	v_lshl_add_u64 v[130:131], v[128:129], 0, s[14:15]
	v_add_co_u32_e32 v128, vcc, s57, v128
	v_lshl_add_u64 v[158:159], s[10:11], 0, v[156:157]
	v_lshlrev_b64 v[230:231], 12, v[214:215]
	v_lshlrev_b64 v[232:233], 12, v[182:183]
	v_addc_co_u32_e32 v129, vcc, 0, v129, vcc
	v_lshl_add_u64 v[178:179], v[158:159], 0, v[230:231]
	v_lshl_add_u64 v[194:195], v[158:159], 0, v[232:233]
	global_load_dwordx4 v[136:139], v[130:131], off offset:64
	global_load_dwordx4 v[132:135], v[130:131], off offset:512
	global_load_dwordx4 v[140:143], v[128:129], off
	s_nop 0
	global_load_dwordx4 v[128:131], v[130:131], off offset:576
	global_load_dwordx4 v[166:169], v[178:179], off
	global_load_dwordx4 v[170:173], v[178:179], off offset:64
	global_load_dwordx4 v[174:177], v[178:179], off offset:512
	s_nop 0
	global_load_dwordx4 v[178:181], v[178:179], off offset:576
	s_nop 0
	global_load_dwordx4 v[182:185], v[194:195], off
	global_load_dwordx4 v[186:189], v[194:195], off offset:64
	global_load_dwordx4 v[190:193], v[194:195], off offset:512
	s_nop 0
	global_load_dwordx4 v[194:197], v[194:195], off offset:576
	v_or_b32_e32 v198, 32, v214
	v_or_b32_e32 v214, 48, v214
	v_ashrrev_i32_e32 v199, 31, v198
	v_ashrrev_i32_e32 v215, 31, v214
	v_lshlrev_b64 v[234:235], 12, v[198:199]
	v_lshlrev_b64 v[236:237], 12, v[214:215]
	v_lshl_add_u64 v[210:211], v[158:159], 0, v[234:235]
	v_lshl_add_u64 v[226:227], v[158:159], 0, v[236:237]
	global_load_dwordx4 v[198:201], v[210:211], off
	global_load_dwordx4 v[202:205], v[210:211], off offset:64
	global_load_dwordx4 v[206:209], v[210:211], off offset:512
	s_nop 0
	global_load_dwordx4 v[210:213], v[210:211], off offset:576
	s_nop 0
	global_load_dwordx4 v[214:217], v[226:227], off
	global_load_dwordx4 v[218:221], v[226:227], off offset:64
	global_load_dwordx4 v[222:225], v[226:227], off offset:512
	s_nop 0
	global_load_dwordx4 v[226:229], v[226:227], off offset:576
	s_waitcnt vmcnt(15)
	v_pk_fma_f32 v[124:125], v[124:125], v[140:141], v[166:167]
	v_lshl_add_u64 v[166:167], s[4:5], 0, v[230:231]
	v_lshl_add_u64 v[166:167], v[166:167], 0, v[156:157]
	s_waitcnt vmcnt(13)
	v_pk_fma_f32 v[114:115], v[114:115], v[134:135], v[176:177]
	v_pk_fma_f32 v[112:113], v[112:113], v[132:133], v[174:175]
	global_store_dwordx4 v[166:167], v[112:115], off offset:512
	s_waitcnt vmcnt(13)
	v_pk_fma_f32 v[106:107], v[106:107], v[130:131], v[180:181]
	v_pk_fma_f32 v[104:105], v[104:105], v[128:129], v[178:179]
	v_lshl_add_u64 v[112:113], s[4:5], 0, v[232:233]
	global_store_dwordx4 v[166:167], v[104:107], off offset:576
	v_lshl_add_u64 v[112:113], v[112:113], 0, v[156:157]
	v_pk_fma_f32 v[126:127], v[126:127], v[142:143], v[168:169]
	s_waitcnt vmcnt(13)
	v_pk_fma_f32 v[106:107], v[118:119], v[142:143], v[184:185]
	v_pk_fma_f32 v[104:105], v[116:117], v[140:141], v[182:183]
	v_pk_fma_f32 v[122:123], v[122:123], v[138:139], v[172:173]
	v_pk_fma_f32 v[120:121], v[120:121], v[136:137], v[170:171]
	global_store_dwordx4 v[112:113], v[104:107], off
	s_waitcnt vmcnt(12)
	v_pk_fma_f32 v[102:103], v[102:103], v[134:135], v[192:193]
	v_pk_fma_f32 v[100:101], v[100:101], v[132:133], v[190:191]
	v_pk_fma_f32 v[106:107], v[110:111], v[138:139], v[188:189]
	v_pk_fma_f32 v[104:105], v[108:109], v[136:137], v[186:187]
	s_waitcnt vmcnt(11)
	v_pk_fma_f32 v[94:95], v[94:95], v[130:131], v[196:197]
	v_pk_fma_f32 v[92:93], v[92:93], v[128:129], v[194:195]
	global_store_dwordx4 v[166:167], v[124:127], off
	global_store_dwordx4 v[166:167], v[120:123], off offset:64
	global_store_dwordx4 v[112:113], v[104:107], off offset:64
	global_store_dwordx4 v[112:113], v[100:103], off offset:512
	global_store_dwordx4 v[112:113], v[92:95], off offset:576
	v_lshl_add_u64 v[166:167], v[230:231], 0, s[16:17]
	v_lshl_add_u64 v[168:169], v[230:231], 0, s[18:19]
	v_lshl_add_u64 v[108:109], v[158:159], 0, v[166:167]
	v_lshl_add_u64 v[124:125], v[158:159], 0, v[168:169]
	global_load_dwordx4 v[92:95], v[108:109], off
	global_load_dwordx4 v[100:103], v[108:109], off offset:64
	global_load_dwordx4 v[104:107], v[108:109], off offset:512
	s_nop 0
	global_load_dwordx4 v[108:111], v[108:109], off offset:576
	s_nop 0
	global_load_dwordx4 v[112:115], v[124:125], off
	global_load_dwordx4 v[116:119], v[124:125], off offset:64
	global_load_dwordx4 v[120:123], v[124:125], off offset:512
	s_nop 0
	global_load_dwordx4 v[124:127], v[124:125], off offset:576
	v_lshl_add_u64 v[170:171], s[4:5], 0, v[234:235]
	v_lshl_add_u64 v[170:171], v[170:171], 0, v[156:157]
	s_waitcnt vmcnt(21)
	v_pk_fma_f32 v[82:83], v[82:83], v[134:135], v[208:209]
	v_pk_fma_f32 v[80:81], v[80:81], v[132:133], v[206:207]
	global_store_dwordx4 v[170:171], v[80:83], off offset:512
	s_waitcnt vmcnt(21)
	v_pk_fma_f32 v[74:75], v[74:75], v[130:131], v[212:213]
	v_pk_fma_f32 v[72:73], v[72:73], v[128:129], v[210:211]
	v_lshl_add_u64 v[80:81], s[4:5], 0, v[236:237]
	global_store_dwordx4 v[170:171], v[72:75], off offset:576
	v_lshl_add_u64 v[80:81], v[80:81], 0, v[156:157]
	v_pk_fma_f32 v[98:99], v[98:99], v[142:143], v[200:201]
	s_waitcnt vmcnt(21)
	v_pk_fma_f32 v[74:75], v[86:87], v[142:143], v[216:217]
	v_pk_fma_f32 v[72:73], v[84:85], v[140:141], v[214:215]
	v_pk_fma_f32 v[96:97], v[96:97], v[140:141], v[198:199]
	v_pk_fma_f32 v[90:91], v[90:91], v[138:139], v[204:205]
	v_pk_fma_f32 v[88:89], v[88:89], v[136:137], v[202:203]
	global_store_dwordx4 v[80:81], v[72:75], off
	s_waitcnt vmcnt(20)
	v_pk_fma_f32 v[70:71], v[70:71], v[134:135], v[224:225]
	v_pk_fma_f32 v[68:69], v[68:69], v[132:133], v[222:223]
	v_pk_fma_f32 v[74:75], v[78:79], v[138:139], v[220:221]
	v_pk_fma_f32 v[72:73], v[76:77], v[136:137], v[218:219]
	s_waitcnt vmcnt(19)
	v_pk_fma_f32 v[66:67], v[66:67], v[130:131], v[228:229]
	v_pk_fma_f32 v[64:65], v[64:65], v[128:129], v[226:227]
	global_store_dwordx4 v[170:171], v[96:99], off
	global_store_dwordx4 v[170:171], v[88:91], off offset:64
	global_store_dwordx4 v[80:81], v[72:75], off offset:64
	global_store_dwordx4 v[80:81], v[68:71], off offset:512
	global_store_dwordx4 v[80:81], v[64:67], off offset:576
	v_lshl_add_u64 v[170:171], v[230:231], 0, s[20:21]
	v_lshl_add_u64 v[172:173], v[230:231], 0, s[22:23]
	v_lshl_add_u64 v[76:77], v[158:159], 0, v[170:171]
	v_lshl_add_u64 v[96:97], v[158:159], 0, v[172:173]
	global_load_dwordx4 v[64:67], v[76:77], off
	global_load_dwordx4 v[68:71], v[76:77], off offset:64
	global_load_dwordx4 v[72:75], v[76:77], off offset:512
	s_nop 0
	global_load_dwordx4 v[76:79], v[76:77], off offset:576
	s_nop 0
	global_load_dwordx4 v[80:83], v[96:97], off
	global_load_dwordx4 v[84:87], v[96:97], off offset:64
	global_load_dwordx4 v[88:91], v[96:97], off offset:512
	s_nop 0
	global_load_dwordx4 v[96:99], v[96:97], off offset:576
	s_waitcnt vmcnt(23)
	v_pk_fma_f32 v[60:61], v[60:61], v[140:141], v[92:93]
	v_lshl_add_u64 v[92:93], s[4:5], 0, v[166:167]
	v_lshl_add_u64 v[92:93], v[92:93], 0, v[156:157]
	s_waitcnt vmcnt(21)
	v_pk_fma_f32 v[50:51], v[50:51], v[134:135], v[106:107]
	v_pk_fma_f32 v[48:49], v[48:49], v[132:133], v[104:105]
	global_store_dwordx4 v[92:93], v[48:51], off offset:512
	s_waitcnt vmcnt(18)
	v_pk_fma_f32 v[34:35], v[34:35], v[134:135], v[122:123]
	v_pk_fma_f32 v[32:33], v[32:33], v[132:133], v[120:121]
	v_lshl_add_u64 v[48:49], s[4:5], 0, v[168:169]
	v_lshl_add_u64 v[48:49], v[48:49], 0, v[156:157]
	global_store_dwordx4 v[48:49], v[32:35], off offset:512
	s_waitcnt vmcnt(7)
	v_pk_fma_f32 v[18:19], v[18:19], v[134:135], v[74:75]
	v_pk_fma_f32 v[16:17], v[16:17], v[132:133], v[72:73]
	v_lshl_add_u64 v[32:33], s[4:5], 0, v[170:171]
	v_lshl_add_u64 v[32:33], v[32:33], 0, v[156:157]
	v_pk_fma_f32 v[42:43], v[42:43], v[130:131], v[110:111]
	v_pk_fma_f32 v[40:41], v[40:41], v[128:129], v[108:109]
	v_pk_fma_f32 v[26:27], v[26:27], v[130:131], v[126:127]
	v_pk_fma_f32 v[24:25], v[24:25], v[128:129], v[124:125]
	global_store_dwordx4 v[32:33], v[16:19], off offset:512
	s_waitcnt vmcnt(7)
	v_pk_fma_f32 v[10:11], v[10:11], v[130:131], v[78:79]
	v_pk_fma_f32 v[8:9], v[8:9], v[128:129], v[76:77]
	v_lshl_add_u64 v[16:17], s[4:5], 0, v[172:173]
	global_store_dwordx4 v[92:93], v[40:43], off offset:576
	global_store_dwordx4 v[48:49], v[24:27], off offset:576
	global_store_dwordx4 v[32:33], v[8:11], off offset:576
	v_pk_fma_f32 v[42:43], v[54:55], v[142:143], v[114:115]
	v_pk_fma_f32 v[40:41], v[52:53], v[140:141], v[112:113]
	v_pk_fma_f32 v[26:27], v[38:39], v[142:143], v[66:67]
	v_pk_fma_f32 v[24:25], v[36:37], v[140:141], v[64:65]
	s_waitcnt vmcnt(9)
	v_pk_fma_f32 v[10:11], v[22:23], v[142:143], v[82:83]
	v_pk_fma_f32 v[8:9], v[20:21], v[140:141], v[80:81]
	v_lshl_add_u64 v[16:17], v[16:17], 0, v[156:157]
	v_pk_fma_f32 v[62:63], v[62:63], v[142:143], v[94:95]
	v_pk_fma_f32 v[58:59], v[58:59], v[138:139], v[102:103]
	v_pk_fma_f32 v[56:57], v[56:57], v[136:137], v[100:101]
	global_store_dwordx4 v[48:49], v[40:43], off
	global_store_dwordx4 v[32:33], v[24:27], off
	global_store_dwordx4 v[16:17], v[8:11], off
	v_pk_fma_f32 v[42:43], v[46:47], v[138:139], v[118:119]
	v_pk_fma_f32 v[40:41], v[44:45], v[136:137], v[116:117]
	v_pk_fma_f32 v[26:27], v[30:31], v[138:139], v[70:71]
	v_pk_fma_f32 v[24:25], v[28:29], v[136:137], v[68:69]
	s_waitcnt vmcnt(11)
	v_pk_fma_f32 v[10:11], v[14:15], v[138:139], v[86:87]
	v_pk_fma_f32 v[8:9], v[12:13], v[136:137], v[84:85]
	s_waitcnt vmcnt(10)
	v_pk_fma_f32 v[6:7], v[6:7], v[134:135], v[90:91]
	v_pk_fma_f32 v[4:5], v[4:5], v[132:133], v[88:89]
	s_waitcnt vmcnt(9)
	v_pk_fma_f32 v[2:3], v[2:3], v[130:131], v[98:99]
	v_pk_fma_f32 v[0:1], v[0:1], v[128:129], v[96:97]
	global_store_dwordx4 v[92:93], v[60:63], off
	global_store_dwordx4 v[92:93], v[56:59], off offset:64
	global_store_dwordx4 v[48:49], v[40:43], off offset:64
	global_store_dwordx4 v[32:33], v[24:27], off offset:64
	global_store_dwordx4 v[16:17], v[8:11], off offset:64
	global_store_dwordx4 v[16:17], v[4:7], off offset:512
	global_store_dwordx4 v[16:17], v[0:3], off offset:576
	s_andn2_b64 vcc, exec, s[0:1]
	s_mov_b64 s[0:1], -1
	s_cbranch_vccnz .LBB0_758
	s_andn2_b64 vcc, exec, s[2:3]
	s_cbranch_vccnz .LBB0_757
	s_barrier
	s_branch .LBB0_757

	.amdhsa_kernel _Z10fwd_kernel6Params
		.amdhsa_group_segment_fixed_size 0
		.amdhsa_private_segment_fixed_size 0
		.amdhsa_kernarg_size 456
		.amdhsa_user_sgpr_count 2
		.amdhsa_user_sgpr_dispatch_ptr 0
		.amdhsa_user_sgpr_queue_ptr 0
		.amdhsa_user_sgpr_kernarg_segment_ptr 1
		.amdhsa_user_sgpr_dispatch_id 0
		.amdhsa_user_sgpr_kernarg_preload_length 0
		.amdhsa_user_sgpr_kernarg_preload_offset 0
		.amdhsa_user_sgpr_private_segment_size 0
		.amdhsa_uses_dynamic_stack 0
		.amdhsa_enable_private_segment 0
		.amdhsa_system_sgpr_workgroup_id_x 1
		.amdhsa_system_sgpr_workgroup_id_y 0
		.amdhsa_system_sgpr_workgroup_id_z 0
		.amdhsa_system_sgpr_workgroup_info 0
		.amdhsa_system_vgpr_workitem_id 0
		.amdhsa_next_free_vgpr 256
		.amdhsa_next_free_sgpr 102
		.amdhsa_accum_offset 256
		.amdhsa_reserve_vcc 1
		.amdhsa_float_round_mode_32 0
		.amdhsa_float_round_mode_16_64 0
		.amdhsa_float_denorm_mode_32 3
		.amdhsa_float_denorm_mode_16_64 3
		.amdhsa_dx10_clamp 1
		.amdhsa_ieee_mode 1
		.amdhsa_fp16_overflow 0
		.amdhsa_tg_split 0
		.amdhsa_exception_fp_ieee_invalid_op 0
		.amdhsa_exception_fp_denorm_src 0
		.amdhsa_exception_fp_ieee_div_zero 0
		.amdhsa_exception_fp_ieee_overflow 0
		.amdhsa_exception_fp_ieee_underflow 0
		.amdhsa_exception_fp_ieee_inexact 0
		.amdhsa_exception_int_div_zero 0
	.end_amdhsa_kernel

amdhsa.kernels:
  - .agpr_count:     0
    .args:
      - .offset:         0
        .size:           200
        .value_kind:     by_value
      - .offset:         200
        .size:           4
        .value_kind:     hidden_block_count_x
      - .offset:         204
        .size:           4
        .value_kind:     hidden_block_count_y
      - .offset:         208
        .size:           4
        .value_kind:     hidden_block_count_z
      - .offset:         212
        .size:           2
        .value_kind:     hidden_group_size_x
      - .offset:         214
        .size:           2
        .value_kind:     hidden_group_size_y
      - .offset:         216
        .size:           2
        .value_kind:     hidden_group_size_z
      - .offset:         218
        .size:           2
        .value_kind:     hidden_remainder_x
      - .offset:         220
        .size:           2
        .value_kind:     hidden_remainder_y
      - .offset:         222
        .size:           2
        .value_kind:     hidden_remainder_z
      - .offset:         240
        .size:           8
        .value_kind:     hidden_global_offset_x
      - .offset:         248
        .size:           8
        .value_kind:     hidden_global_offset_y
      - .offset:         256
        .size:           8
        .value_kind:     hidden_global_offset_z
      - .offset:         264
        .size:           2
        .value_kind:     hidden_grid_dims
      - .offset:         320
        .size:           4
        .value_kind:     hidden_dynamic_lds_size
    .group_segment_fixed_size: 0
    .kernarg_segment_align: 8
    .kernarg_segment_size: 456
    .language:       OpenCL C
    .language_version:
      - 2
      - 0
    .max_flat_workgroup_size: 512
    .name:           _Z10fwd_kernel6Params
    .private_segment_fixed_size: 0
    .sgpr_count:     108
    .sgpr_spill_count: 258
    .symbol:         _Z10fwd_kernel6Params.kd
    .uniform_work_group_size: 1
    .uses_dynamic_stack: false
    .vgpr_count:     256
    .vgpr_spill_count: 0
    .wavefront_size: 64
